# loop-edge (7.11): attention A loop-carried updates and next-step K-slot address math moved ahead of the barriers (post-barrier path starts with the ds_reads)
# baseline (speedup 1.0000x reference)
; #define SBAR() __builtin_amdgcn_sched_barrier(0)
; template <int OFF> __device__ __forceinline__ s16x4 tr_read(int vb) { s16x4 r; asm volatile("ds_read_b64_tr_b16 %0, %1 offset:%2" : "=&v"(r) : "v"(vb), "i"(OFF) : "memory"); return r; }
; __device__ __forceinline__ void finishSM(f32x16& p0, f32x16& p1, float alpha, float& l_reg, bf16x8& pa0, bf16x8& pa1, bf16x8& pa2, bf16x8& pa3) {
; #pragma unroll
;   for (int r = 0; r < 16; ++r) p1[r] = __builtin_amdgcn_exp2f(p1[r]);
;   float ps = 0;
; #pragma unroll
;   for (int r = 0; r < 16; ++r) ps += p0[r];
; #pragma unroll
;   for (int r = 0; r < 16; ++r) ps += p1[r];
;   { auto rr = __builtin_amdgcn_permlane32_swap(__float_as_uint(ps), __float_as_uint(ps), false, false);
;     ps = __uint_as_float(rr[0]) + __uint_as_float(rr[1]); }
;   l_reg = l_reg * alpha + ps;
;     ...
;   ATT_PKN(p0, 0, pa0); ATT_PKN(p0, 8, pa1); ATT_PKN(p1, 0, pa2); ATT_PKN(p1, 8, pa3);
;     ...
; }
; __device__ __forceinline__ void qkt(f32x16& p0, f32x16& p1, const bf16* Ks, const bf16x8* qr, int r32, int hi, int mp, const f32x16& negm) {
; #pragma unroll
;   for (int d0 = 0; d0 < 4; ++d0) { int cb = ((mp * 4 + d0) * 16 + hi * 8) * 2;
;     bf16x8 b0 = *reinterpret_cast<const bf16x8*>((const char*)Ks + KSWZ(r32, cb));
;     bf16x8 b1 = *reinterpret_cast<const bf16x8*>((const char*)Ks + KSWZ(32 + r32, cb));
;     if (d0 == 0) { p0 = __builtin_amdgcn_mfma_f32_32x32x16_bf16(b0, qr[0], negm, 0, 0, 0); p1 = __builtin_amdgcn_mfma_f32_32x32x16_bf16(b1, qr[0], negm, 0, 0, 0); }
;     else { p0 = __builtin_amdgcn_mfma_f32_32x32x16_bf16(b0, qr[d0], p0, 0, 0, 0); p1 = __builtin_amdgcn_mfma_f32_32x32x16_bf16(b1, qr[d0], p1, 0, 0, 0); } }
; }
; __device__ __forceinline__ int v_st(int k, int c) { const int kk = k; return ((kk >> 3) * 4 + (c >> 5)) * 512 + ((kk & 7) * 32 + (c & 31)) * 2; }
; template <int D0> __device__ __forceinline__ void pv_one(f32x16& od, int vb, bf16x8 pa0, bf16x8 pa1, bf16x8 pa2, bf16x8 pa3) {
;   const s16x4 l0 = tr_read<v_rd_off(D0, 0, 0)>(vb), h0 = tr_read<v_rd_off(D0, 0, 1)>(vb), l1 = tr_read<v_rd_off(D0, 1, 0)>(vb), h1 = tr_read<v_rd_off(D0, 1, 1)>(vb);
;   const s16x4 l2 = tr_read<v_rd_off(D0, 2, 0)>(vb), h2 = tr_read<v_rd_off(D0, 2, 1)>(vb), l3 = tr_read<v_rd_off(D0, 3, 0)>(vb), h3 = tr_read<v_rd_off(D0, 3, 1)>(vb);
;   asm volatile("s_waitcnt lgkmcnt(0)" ::: "memory"); SBAR();
.LBB0_202:
	v_exp_f32_e32 v211, v128
	v_exp_f32_e32 v213, v129
	v_exp_f32_e32 v214, v130
	v_exp_f32_e32 v217, v131
	v_exp_f32_e32 v232, v132
	v_exp_f32_e32 v235, v133
	v_exp_f32_e32 v236, v134
	v_exp_f32_e32 v239, v135
	v_exp_f32_e32 v212, v136
	v_exp_f32_e32 v215, v137
	v_exp_f32_e32 v216, v138
	v_exp_f32_e32 v233, v139
	v_exp_f32_e32 v234, v140
	v_exp_f32_e32 v237, v141
	v_exp_f32_e32 v238, v142
	v_exp_f32_e32 v240, v143
	s_add_i32 s10, s39, 0x8000
	s_and_b32 s48, s10, 0x1ffff
	s_add_i32 s10, s48, 0
	v_add_u32_e32 v96, s10, v202
	v_add_u32_e32 v241, s10, v201
	s_waitcnt vmcnt(4) lgkmcnt(0)
	s_barrier
	ds_read_b128 v[242:245], v96 offset:24576
	ds_read_b128 v[96:99], v96 offset:16384
	v_exp_f32_e32 v112, v112
	v_exp_f32_e32 v115, v115
	v_exp_f32_e32 v116, v116
	s_waitcnt lgkmcnt(0)
	v_mfma_f32_32x32x16_bf16 v[128:143], v[96:99], v[158:161], v[80:95]
	v_exp_f32_e32 v117, v117
	v_exp_f32_e32 v118, v118
	v_mfma_f32_32x32x16_bf16 v[96:111], v[242:245], v[158:161], v[80:95]
	ds_read_b128 v[242:245], v241 offset:24576
	ds_read_b128 v[246:249], v241 offset:16384
	v_add_u32_e32 v241, s10, v199
	ds_read_b128 v[68:71], v241 offset:24576
	ds_read_b128 v[72:75], v241 offset:16384
	v_add_u32_e32 v241, s10, v183
	s_waitcnt lgkmcnt(2)
	v_mfma_f32_32x32x16_bf16 v[128:143], v[246:249], v[154:157], v[128:143]
	v_mfma_f32_32x32x16_bf16 v[96:111], v[242:245], v[154:157], v[96:111]
	ds_read_b128 v[242:245], v241 offset:24576
	ds_read_b128 v[246:249], v241 offset:16384
	s_waitcnt lgkmcnt(2)
	v_mfma_f32_32x32x16_bf16 v[128:143], v[72:75], v[150:153], v[128:143]
	v_mfma_f32_32x32x16_bf16 v[96:111], v[68:71], v[150:153], v[96:111]
	v_exp_f32_e32 v241, v113
	v_add_f32_e32 v113, v213, v211
	v_add_f32_e32 v113, v214, v113
	v_add_f32_e32 v113, v217, v113
	v_add_f32_e32 v113, v232, v113
	v_add_f32_e32 v113, v235, v113
	v_add_f32_e32 v113, v236, v113
	v_add_f32_e32 v113, v239, v113
	v_add_f32_e32 v113, v212, v113
	v_add_f32_e32 v113, v215, v113
	v_add_f32_e32 v113, v216, v113
	v_add_f32_e32 v113, v233, v113
	v_add_f32_e32 v113, v234, v113
	v_add_f32_e32 v113, v237, v113
	s_waitcnt lgkmcnt(0)
	v_mfma_f32_32x32x16_bf16 v[96:111], v[242:245], v[146:149], v[96:111]
	v_exp_f32_e32 v242, v114
	v_add_f32_e32 v113, v238, v113
	v_add_f32_e32 v113, v240, v113
	v_add_f32_e32 v113, v112, v113
	v_add_f32_e32 v113, v241, v113
	v_add_f32_e32 v113, v242, v113
	v_exp_f32_e32 v243, v119
	v_add_f32_e32 v113, v115, v113
	v_exp_f32_e32 v119, v120
	v_add_f32_e32 v113, v116, v113
	v_exp_f32_e32 v120, v121
	v_add_f32_e32 v113, v117, v113
	v_exp_f32_e32 v121, v122
	v_add_f32_e32 v113, v118, v113
	v_exp_f32_e32 v122, v123
	v_add_f32_e32 v113, v243, v113
	v_exp_f32_e32 v123, v124
	v_add_f32_e32 v113, v119, v113
	v_exp_f32_e32 v124, v125
	v_add_f32_e32 v113, v120, v113
	v_mfma_f32_32x32x16_bf16 v[128:143], v[246:249], v[146:149], v[128:143]
	v_exp_f32_e32 v125, v126
	v_add_f32_e32 v113, v121, v113
	v_exp_f32_e32 v126, v127
	v_add_f32_e32 v113, v122, v113
	v_add_f32_e32 v113, v123, v113
	v_add_f32_e32 v113, v124, v113
	v_add_f32_e32 v113, v125, v113
	v_add_f32_e32 v113, v126, v113
	v_mov_b32_e32 v114, v113
	s_nop 1
	v_permlane32_swap_b32_e32 v113, v114
	v_cvt_pk_bf16_f32 v250, v211, v213
	v_cvt_pk_bf16_f32 v251, v214, v217
	v_cvt_pk_bf16_f32 v252, v232, v235
	v_cvt_pk_bf16_f32 v253, v236, v239
	v_cvt_pk_bf16_f32 v212, v212, v215
	v_cvt_pk_bf16_f32 v213, v216, v233
	v_cvt_pk_bf16_f32 v214, v234, v237
	v_cvt_pk_bf16_f32 v215, v238, v240
	v_cvt_pk_bf16_f32 v232, v112, v241
	v_cvt_pk_bf16_f32 v233, v242, v115
	v_cvt_pk_bf16_f32 v234, v116, v117
	v_cvt_pk_bf16_f32 v235, v118, v243
	v_cvt_pk_bf16_f32 v116, v119, v120
	v_cvt_pk_bf16_f32 v117, v121, v122
	v_cvt_pk_bf16_f32 v118, v123, v124
	v_cvt_pk_bf16_f32 v119, v125, v126
	v_add_u32_e32 v112, s39, v205
	ds_read_b64_tr_b16 v[120:121], v112 offset:0
	ds_read_b64_tr_b16 v[122:123], v112 offset:0x800
	ds_read_b64_tr_b16 v[124:125], v112 offset:0x1000
	ds_read_b64_tr_b16 v[126:127], v112 offset:0x1800
	ds_read_b64_tr_b16 v[236:237], v112 offset:0x2000
	ds_read_b64_tr_b16 v[238:239], v112 offset:0x2800
	ds_read_b64_tr_b16 v[240:241], v112 offset:0x3000
	ds_read_b64_tr_b16 v[242:243], v112 offset:0x3800
	s_cmp_gt_u32 s44, 60
	s_cselect_b64 s[52:53], -1, 0
	s_and_b64 vcc, exec, s[52:53]
	s_cbranch_vccnz .LBB0_204
	s_add_i32 s10, s56, 0x8000
	s_and_b32 s10, s10, 0x1ffff
	s_add_i32 s12, s21, s10
	s_add_u32 s98, s50, s68
	s_addc_u32 s99, s51, s69
	s_add_u32 s100, s50, 0x4040000
	s_addc_u32 s101, s51, 0
	s_add_i32 m0, s12, 0x4000
	s_add_u32 s10, s100, 0x80
	s_addc_u32 s11, s101, 0
	global_load_lds_dwordx4 v168, s[98:99]
	s_mov_b32 m0, s12
	s_nop 0
	global_load_lds_dwordx4 v188, s[100:101]
	s_add_i32 m0, s12, 0x4400
	s_nop 0
	global_load_lds_dwordx4 v170, s[98:99]
	s_add_i32 m0, s12, 0x400
	s_nop 0
	global_load_lds_dwordx4 v188, s[10:11]

; template <bool FIRST> __device__ __forceinline__ void partialSM(f32x16& p0, f32x16& p1, float& m_reg, f32x16& negm, float& alpha) {
;     ...
;   if (FIRST || __builtin_expect(__any(pmax > THR), 0)) { const float dl = FIRST ? pmax : fmaxf(pmax, 0.f); m_reg += dl; if (!FIRST) alpha = __builtin_amdgcn_exp2f(-dl);
; #pragma unroll
;     for (int r = 0; r < 16; ++r) { p0[r] -= dl; p1[r] -= dl; }
; #pragma unroll
;     for (int r = 0; r < 16; ++r) negm[r] = -m_reg; }
; #pragma unroll
;   for (int r = 0; r < 16; ++r) p0[r] = __builtin_amdgcn_exp2f(p0[r]);
; }
; __device__ __forceinline__ void finishSM(f32x16& p0, f32x16& p1, float alpha, float& l_reg, bf16x8& pa0, bf16x8& pa1, bf16x8& pa2, bf16x8& pa3) {
; #pragma unroll
;   for (int r = 0; r < 16; ++r) p1[r] = __builtin_amdgcn_exp2f(p1[r]);
;   float ps = 0;
; #pragma unroll
;   for (int r = 0; r < 16; ++r) ps += p0[r];
; #pragma unroll
;   for (int r = 0; r < 16; ++r) ps += p1[r];
;   { auto rr = __builtin_amdgcn_permlane32_swap(__float_as_uint(ps), __float_as_uint(ps), false, false);
;     ps = __uint_as_float(rr[0]) + __uint_as_float(rr[1]); }
;   l_reg = l_reg * alpha + ps;
; __device__ __forceinline__ void unit(const bf16* Qb, const bf16* __restrict__ Kh, const bf16* __restrict__ Vh, bf16* Ob, float lam, float post, const float* __restrict__ gsub, char* lds) {
;     ...
;   for (int j = 1; j + 1 < NT; j += 2) {
;     A_STEP(pB0, pB1, pA0, pA1, alB, alA, j);
;     A_STEP(pA0, pA1, pB0, pB1, alA, alB, j + 1);
;   }
.LBB0_213:
	v_exp_f32_e32 v172, v128
	v_exp_f32_e32 v174, v129
	v_exp_f32_e32 v175, v130
	v_exp_f32_e32 v211, v131
	v_exp_f32_e32 v212, v132
	v_exp_f32_e32 v215, v133
	v_exp_f32_e32 v216, v134
	v_exp_f32_e32 v233, v135
	v_exp_f32_e32 v173, v136
	v_exp_f32_e32 v176, v137
	v_exp_f32_e32 v177, v138
	v_exp_f32_e32 v213, v139
	v_exp_f32_e32 v214, v140
	v_exp_f32_e32 v217, v141
	v_exp_f32_e32 v232, v142
	v_exp_f32_e32 v234, v143
	v_add_f32_e32 v115, v208, v209
	s_add_i32 s44, s44, 2
	s_xor_b32 s39, s39, 0x10000
	s_xor_b32 s56, s56, 0x10000
	v_fmac_f32_e32 v115, v207, v180
	v_add_f32_e32 v180, v113, v114
	s_add_u32 s50, s50, 0x20000
	v_fmac_f32_e32 v180, v115, v210
	s_addc_u32 s51, s51, 0
	s_and_b64 vcc, exec, s[52:53]
	v_mov_b32_e32 v207, v112
	s_barrier
	s_cbranch_vccnz .LBB0_217
	s_branch .LBB0_197
